# hg_item(true) pre-loop: chunk-0 log-gate loads land in 8 distinct registers, one wait + converts before the loop (was 8 serialized load->wait->convert round trips through v39)
# baseline (speedup 1.0000x reference)
; template <bool FULL, bool STORE = true>
; __device__ __forceinline__ void hg_item(const Prm& P, LAS unsigned char* lds, int item, int wave) {
;     ...
;     HG_LOADS(0);
.LBB0_838:
	s_or_b64 exec, exec, s[18:19]
	s_ashr_i32 s84, s91, 6
	s_and_b32 s18, s2, 7
	s_ashr_i32 s85, s84, 31
	s_lshl_b32 s33, s18, 21
	s_lshl_b32 s19, s54, 1
	s_lshl_b32 s87, s18, 10
	s_lshl_b64 s[52:53], s[84:85], 13
	s_lshl_b32 s18, s26, 10
	s_and_b32 s86, s19, 0x700
	s_or_b32 s18, s52, s18
	s_add_u32 s20, s18, s55
	v_lshlrev_b32_e32 v36, 1, v32
	s_addc_u32 s21, s53, 0
	s_lshl_b32 s22, s91, 4
	s_and_b32 s74, s22, 0x380
	v_ashrrev_i32_e32 v37, 31, v36
	v_lshl_add_u64 v[76:77], v[36:37], 0, s[74:75]
	s_lshl_b64 s[20:21], s[20:21], 10
	v_lshl_add_u64 v[44:45], v[76:77], 0, s[20:21]
	v_lshlrev_b64 v[44:45], 1, v[44:45]
	v_lshl_add_u64 v[46:47], s[70:71], 0, v[44:45]
	global_load_dword v240, v[46:47], off nt
	v_lshl_add_u64 v[48:49], s[62:63], 0, v[44:45]
	global_load_dword v110, v[48:49], off nt
	v_lshl_add_u64 v[48:49], s[64:65], 0, v[44:45]
	s_mov_b64 s[20:21], 0x800
	v_ashrrev_i32_e32 v38, 3, v38
	s_mov_b32 s19, s53
	v_lshlrev_b32_e32 v43, 4, v32
	v_and_b32_e32 v94, 0x70, v43
	v_lshlrev_b32_e32 v74, 1, v94
	v_and_b32_e32 v60, 64, v108
	v_xor_b32_e32 v59, 1, v108
	v_add_u32_e32 v60, 64, v60
	v_cmp_lt_i32_e32 vcc, v59, v60
	v_lshlrev_b32_e32 v128, 4, v40
	v_readlane_b32 s46, v255, 48
	v_cndmask_b32_e32 v59, v108, v59, vcc
	v_lshlrev_b32_e32 v129, 2, v59
	v_xor_b32_e32 v59, 2, v108
	v_cmp_lt_i32_e32 vcc, v59, v60
	v_readlane_b32 s22, v255, 37
	v_readlane_b32 s24, v255, 38
	v_cndmask_b32_e32 v59, v108, v59, vcc
	v_lshlrev_b32_e32 v130, 2, v59
	v_xor_b32_e32 v59, 4, v108
	v_cmp_lt_i32_e32 vcc, v59, v60
	v_readlane_b32 s26, v255, 39
	v_readlane_b32 s28, v255, 40
	v_cndmask_b32_e32 v59, v108, v59, vcc
	v_readlane_b32 s30, v255, 41
	v_readlane_b32 s34, v255, 42
	v_readlane_b32 s36, v255, 43
	v_readlane_b32 s38, v255, 44
	v_readlane_b32 s40, v255, 45
	v_readlane_b32 s42, v255, 46
	v_readlane_b32 s44, v255, 47
	v_add_u32_e32 v96, s46, v34
	v_readlane_b32 s48, v255, 49
	v_readlane_b32 s50, v255, 50
	v_add_u32_e32 v61, s97, v34
	v_add_u32_e32 v63, s22, v34
	v_add_u32_e32 v64, s24, v34
	v_add_u32_e32 v65, s26, v34
	v_add_u32_e32 v66, s28, v34
	v_add_u32_e32 v67, s30, v34
	v_add_u32_e32 v68, s34, v34
	v_add_u32_e32 v69, s36, v34
	v_add_u32_e32 v70, s38, v34
	v_add_u32_e32 v71, s40, v34
	v_add_u32_e32 v72, s42, v34
	v_add_u32_e32 v73, s44, v34
	v_mul_lo_u32 v102, v96, s72
	v_lshlrev_b32_e32 v131, 2, v59
	v_or_b32_e32 v59, s97, v42
	v_lshlrev_b32_e32 v126, 3, v32
	v_mul_lo_u32 v58, v38, s94
	v_mul_u32_u24_e32 v41, 0x110, v33
	v_add_u32_e32 v58, 0, v58
	v_mad_u32_u24 v59, v59, s3, 0
	v_add_u32_e32 v133, v59, v128
	v_add_u32_e32 v156, v35, v41
	global_load_dword v111, v[48:49], off nt
	global_load_dword v241, v[46:47], off offset:2048 nt
	v_lshl_add_u64 v[46:47], v[44:45], 0, s[20:21]
	v_lshl_add_u64 v[48:49], s[62:63], 0, v[46:47]
	v_lshl_add_u64 v[46:47], s[64:65], 0, v[46:47]
	s_mov_b64 s[20:21], 0x1000
	global_load_dword v112, v[48:49], off nt
	global_load_dword v113, v[46:47], off nt
	v_lshl_add_u64 v[46:47], v[44:45], 0, s[20:21]
	v_lshl_add_u64 v[48:49], s[70:71], 0, v[46:47]
	s_mov_b64 s[20:21], 0x1800
	global_load_dword v242, v[48:49], off nt
	v_lshl_add_u64 v[48:49], s[62:63], 0, v[46:47]
	v_lshl_add_u64 v[46:47], s[64:65], 0, v[46:47]
	global_load_dword v114, v[48:49], off nt
	global_load_dword v115, v[46:47], off nt
	v_lshl_add_u64 v[46:47], v[44:45], 0, s[20:21]
	v_lshl_add_u64 v[48:49], s[70:71], 0, v[46:47]
	s_mov_b64 s[20:21], 0x2000
	global_load_dword v243, v[48:49], off nt
	v_lshl_add_u64 v[48:49], s[62:63], 0, v[46:47]
	v_lshl_add_u64 v[46:47], s[64:65], 0, v[46:47]
	global_load_dword v116, v[48:49], off nt
	global_load_dword v117, v[46:47], off nt
	v_lshl_add_u64 v[46:47], v[44:45], 0, s[20:21]
	v_lshl_add_u64 v[48:49], s[70:71], 0, v[46:47]
	s_mov_b64 s[20:21], 0x2800
	global_load_dword v244, v[48:49], off nt
	v_lshl_add_u64 v[48:49], s[62:63], 0, v[46:47]
	v_lshl_add_u64 v[46:47], s[64:65], 0, v[46:47]
	global_load_dword v118, v[48:49], off nt
	global_load_dword v119, v[46:47], off nt
	v_lshl_add_u64 v[46:47], v[44:45], 0, s[20:21]
	v_lshl_add_u64 v[48:49], s[70:71], 0, v[46:47]
	s_mov_b64 s[20:21], 0x3000
	global_load_dword v245, v[48:49], off nt
	v_lshl_add_u64 v[48:49], s[62:63], 0, v[46:47]
	v_lshl_add_u64 v[46:47], s[64:65], 0, v[46:47]
	global_load_dword v120, v[48:49], off nt
	global_load_dword v121, v[46:47], off nt
	v_lshl_add_u64 v[46:47], v[44:45], 0, s[20:21]
	v_lshl_add_u64 v[48:49], s[70:71], 0, v[46:47]
	s_mov_b64 s[20:21], 0x3800
	v_lshl_add_u64 v[44:45], v[44:45], 0, s[20:21]
	v_readlane_b32 s20, v255, 36
	global_load_dword v246, v[48:49], off nt
	v_lshl_add_u64 v[48:49], s[62:63], 0, v[46:47]
	v_lshl_add_u64 v[46:47], s[64:65], 0, v[46:47]
	global_load_dword v122, v[48:49], off nt
	global_load_dword v123, v[46:47], off nt
	v_lshl_add_u64 v[46:47], s[70:71], 0, v[44:45]
	v_add_u32_e32 v62, s20, v34
	global_load_dword v247, v[46:47], off nt
	v_lshl_add_u64 v[46:47], s[62:63], 0, v[44:45]
	v_lshl_add_u64 v[44:45], s[64:65], 0, v[44:45]
	global_load_dword v124, v[46:47], off nt
	global_load_dword v125, v[44:45], off nt
	v_lshlrev_b32_e32 v47, 2, v32
	v_ashrrev_i32_e32 v39, 31, v38
; template <bool FULL, bool STORE = true>
; __device__ __forceinline__ void hg_item(const Prm& P, LAS unsigned char* lds, int item, int wave) {
;     ...
;     HG_LOADS(0);
	v_lshl_add_u64 v[44:45], s[18:19], 0, v[38:39]
	v_lshlrev_b64 v[44:45], 11, v[44:45]
	v_lshl_add_u64 v[44:45], s[66:67], 0, v[44:45]
	s_lshl_b32 s18, s74, 1
	s_mov_b32 s19, s75
	v_lshl_add_u64 v[44:45], v[44:45], 0, s[18:19]
	v_lshl_add_u64 v[44:45], v[44:45], 0, v[74:75]
	global_load_dwordx4 v[48:51], v[44:45], off offset:16 nt
	global_load_dwordx4 v[52:55], v[44:45], off nt
	s_movk_i32 s18, 0x120
	v_mul_lo_u32 v127, v32, s18
	v_readlane_b32 s18, v255, 32
	s_add_i32 s19, 0, 0x15c00
	s_lshl_b32 s74, s74, 2
	v_or_b32_e32 v45, s18, v42
	s_add_i32 s18, 0, 0x11400
	v_mov_b32_e32 v40, s18
	v_add_u32_e32 v57, s18, v128
	v_readlane_b32 s18, v255, 34
	v_mov_b32_e32 v46, s19
	v_add_u32_e32 v74, s59, v34
	v_readlane_b32 s19, v255, 33
	v_or_b32_e32 v95, s18, v42
	s_add_u32 vcc_lo, s82, s74
	v_mad_u32_u24 v40, v45, s72, v40
	v_mad_u32_u24 v45, v45, s3, v46
	v_lshl_add_u32 v46, v42, 2, s19
	v_readlane_b32 s19, v255, 29
	v_cmp_gt_i32_e64 s[46:47], v95, v96
	v_add_u32_e32 v96, s48, v34
	v_add_u32_e32 v34, s50, v34
	v_mul_lo_u32 v104, v74, s94
	v_lshlrev_b32_e32 v74, 2, v94
	s_addc_u32 vcc_hi, s83, 0
	v_or_b32_e32 v44, s59, v42
	v_or_b32_e32 v56, s19, v42
	v_mad_u32_u24 v60, v95, s3, 0
	v_lshl_add_u32 v42, v95, 1, s73
	v_cmp_gt_i32_e64 s[18:19], v95, v61
	v_cmp_gt_i32_e64 s[20:21], v95, v62
	v_cmp_gt_i32_e64 s[22:23], v95, v63
	v_cmp_gt_i32_e64 s[24:25], v95, v64
	v_cmp_gt_i32_e64 s[26:27], v95, v65
	v_cmp_gt_i32_e64 s[28:29], v95, v66
	v_cmp_gt_i32_e64 s[30:31], v95, v67
	v_cmp_gt_i32_e64 s[34:35], v95, v68
	v_cmp_gt_i32_e64 s[36:37], v95, v69
	v_cmp_gt_i32_e64 s[38:39], v95, v70
	v_cmp_gt_i32_e64 s[40:41], v95, v71
	v_cmp_gt_i32_e64 s[42:43], v95, v72
	v_cmp_gt_i32_e64 s[44:45], v95, v73
	v_cmp_gt_i32_e64 s[48:49], v95, v96
	v_cmp_gt_i32_e64 s[50:51], v95, v34
	v_lshl_add_u64 v[94:95], vcc, 0, v[74:75]
	s_lshl_b64 vcc, s[84:85], 24
	s_or_b32 vcc_lo, vcc_lo, s33
	v_readlane_b32 s33, v255, 55
	s_add_u32 s33, s33, s52
	s_addc_u32 s53, s90, s53
	v_lshlrev_b64 v[38:39], 11, v[38:39]
	v_and_b32_e32 v32, 7, v32
	s_add_u32 s52, s33, s87
	v_lshl_add_u64 v[38:39], vcc, 0, v[38:39]
	v_lshlrev_b32_e32 v32, 5, v32
	s_addc_u32 s53, s53, 0
	s_or_b32 s33, vcc_lo, s86
	v_mul_lo_u32 v43, v44, s72
	v_mul_lo_u32 v44, v44, s3
	v_mul_lo_u32 v56, v56, s72
	v_mul_lo_u32 v105, v34, s72
	v_mul_u32_u24_e32 v34, 0x90, v33
	v_or3_b32 v38, v38, s86, v32
	v_mov_b32_e32 v32, s33
	v_mov_b32_e32 v33, vcc_hi
	v_add_u32_e32 v43, s73, v43
	v_add_u32_e32 v44, 0, v44
	v_add_u32_e32 v56, 0, v56
	v_mul_lo_u32 v61, v61, s72
	v_mul_lo_u32 v62, v62, s72
	v_mul_lo_u32 v63, v63, s72
	v_mul_lo_u32 v64, v64, s72
	v_mul_lo_u32 v65, v65, s72
	v_mul_lo_u32 v66, v66, s72
	v_mul_lo_u32 v67, v67, s72
	v_mul_lo_u32 v68, v68, s72
	v_mul_lo_u32 v69, v69, s72
	v_mul_lo_u32 v70, v70, s72
	v_mul_lo_u32 v71, v71, s72
	v_mul_lo_u32 v72, v72, s72
	v_mul_lo_u32 v73, v73, s72
	v_mul_lo_u32 v103, v96, s72
	v_lshl_add_u64 v[32:33], v[36:37], 1, v[32:33]
	v_readlane_b32 s33, v255, 51
	v_lshl_add_u64 v[96:97], s[92:93], 0, v[38:39]
	s_lshl_b64 s[84:85], s[52:53], 10
	v_lshl_add_u64 v[98:99], s[78:79], 0, v[32:33]
	v_lshl_add_u64 v[100:101], s[80:81], 0, v[32:33]
	s_mov_b64 s[86:87], 0
	v_add_u32_e32 v132, s33, v47
	v_add_u32_e32 v134, v60, v128
	v_add_u32_e32 v135, v42, v61
	v_add_u32_e32 v136, v42, v62
	v_add_u32_e32 v137, v42, v63
	v_add_u32_e32 v138, v42, v64
	v_add_u32_e32 v139, v42, v65
	v_add_u32_e32 v140, v42, v66
	v_add_u32_e32 v141, v42, v67
	v_add_u32_e32 v142, v42, v68
	v_add_u32_e32 v143, v42, v69
	v_add_u32_e32 v144, v42, v70
	v_add_u32_e32 v145, v42, v71
	v_add_u32_e32 v146, v42, v72
	v_add_u32_e32 v147, v42, v73
	v_add_u32_e32 v148, v42, v102
	v_add_u32_e32 v149, v42, v103
	v_add_u32_e32 v150, v42, v105
	v_add_u32_e32 v151, v44, v128
	v_add_u32_e32 v152, v45, v128
	v_add_u32_e32 v153, v46, v104
	v_add_u32_e32 v154, v56, v128
	v_add_u32_e32 v155, v57, v34
	v_add_u32_e32 v157, v58, v74
	v_add_u32_e32 v158, v43, v128
	v_add_u32_e32 v159, v40, v128
	global_load_dwordx4 v[224:227], v[94:95], off offset:48
	global_load_dwordx4 v[228:231], v[94:95], off offset:32
	global_load_dwordx4 v[232:235], v[94:95], off offset:16
	global_load_dwordx4 v[236:239], v[94:95], off
	s_waitcnt vmcnt(8)
	v_cvt_f32_f16_e32 v78, v240
	v_cvt_f32_f16_sdwa v79, v240 dst_sel:DWORD dst_unused:UNUSED_PAD src0_sel:WORD_1
	v_cvt_f32_f16_e32 v80, v241
	v_cvt_f32_f16_sdwa v81, v241 dst_sel:DWORD dst_unused:UNUSED_PAD src0_sel:WORD_1
	v_cvt_f32_f16_e32 v82, v242
	v_cvt_f32_f16_sdwa v83, v242 dst_sel:DWORD dst_unused:UNUSED_PAD src0_sel:WORD_1
	v_cvt_f32_f16_e32 v84, v243
	v_cvt_f32_f16_sdwa v85, v243 dst_sel:DWORD dst_unused:UNUSED_PAD src0_sel:WORD_1
	v_cvt_f32_f16_e32 v86, v244
	v_cvt_f32_f16_sdwa v87, v244 dst_sel:DWORD dst_unused:UNUSED_PAD src0_sel:WORD_1
	v_cvt_f32_f16_e32 v88, v245
	v_cvt_f32_f16_sdwa v89, v245 dst_sel:DWORD dst_unused:UNUSED_PAD src0_sel:WORD_1
	v_cvt_f32_f16_e32 v90, v246
	v_cvt_f32_f16_sdwa v91, v246 dst_sel:DWORD dst_unused:UNUSED_PAD src0_sel:WORD_1
	v_cvt_f32_f16_e32 v92, v247
	v_cvt_f32_f16_sdwa v93, v247 dst_sel:DWORD dst_unused:UNUSED_PAD src0_sel:WORD_1
	s_branch .LBB0_840
